# speedup vs baseline: 1.0058x; 1.0034x over previous
; DEV int lv(int x) { asm volatile("" : "+v"(x)); return x; }
; DEV void cvt_weights(const Params& p, int layer) {
;     ...
;   float* tile = (float*)shm_raw;
;   const int t = lv(threadIdx.x), nl = t & 63, kl0 = t >> 6;
;   const int nl2 = t >> 3, kc = (t & 7) * 16;
;   float r[16];
;   int u = blockIdx.x;
;   if (u >= TOT) return;
;   CvtJob j = cvt_job(p, layer, u);
; #pragma unroll
;   for (int i = 0; i < 16; ++i) r[i] = j.W[(size_t)(j.tk * 128 + kl0 + 8 * i) * j.N + j.tn * 64 + nl];
;     ...
;     { const int n = c.tn * 64 + nl2; float cs = 1.f; int row = n;
;       if (c.kind == 0) { if (n < 1024) cs = LOG2E * 0.08838834764831845f; else if (n >= 3072 && n < 4096) cs = LOG2E * 0.125f; }
.LBB0_21:
	s_lshl_b32 s8, s23, 6
	s_ashr_i32 s9, s8, 31
	v_ashrrev_i32_e32 v21, 6, v2
	s_lshl_b64 s[8:9], s[8:9], 2
	v_and_b32_e32 v20, 63, v2
	v_lshl_add_u32 v3, s20, 7, v21
	s_add_u32 s6, s6, s8
	v_mov_b32_e32 v1, 0
	s_addc_u32 s7, s7, s9
	v_lshlrev_b32_e32 v0, 2, v20
	v_ashrrev_i32_e32 v4, 31, v3
	v_lshl_add_u64 v[12:13], s[6:7], 0, v[0:1]
	v_mul_lo_u32 v6, s4, v4
	v_mul_lo_u32 v7, s5, v3
	v_mad_u64_u32 v[4:5], s[6:7], s4, v3, 0
	v_add3_u32 v5, v5, v6, v7
	v_add_u32_e32 v6, 8, v3
	v_ashrrev_i32_e32 v7, 31, v6
	v_mul_lo_u32 v8, s4, v7
	v_mul_lo_u32 v9, s5, v6
	v_mad_u64_u32 v[6:7], s[6:7], s4, v6, 0
	v_add3_u32 v7, v7, v8, v9
	v_add_u32_e32 v8, 16, v3
	v_ashrrev_i32_e32 v9, 31, v8
	v_mul_lo_u32 v10, s4, v9
	v_mul_lo_u32 v11, s5, v8
	v_mad_u64_u32 v[8:9], s[6:7], s4, v8, 0
	v_add3_u32 v9, v9, v10, v11
	v_add_u32_e32 v10, 24, v3
	v_ashrrev_i32_e32 v11, 31, v10
	v_mul_lo_u32 v14, s4, v11
	v_mul_lo_u32 v15, s5, v10
	v_mad_u64_u32 v[10:11], s[6:7], s4, v10, 0
	v_add3_u32 v11, v11, v14, v15
	v_add_u32_e32 v14, 32, v3
	v_ashrrev_i32_e32 v15, 31, v14
	v_mul_lo_u32 v16, s4, v15
	v_mul_lo_u32 v17, s5, v14
	v_mad_u64_u32 v[14:15], s[6:7], s4, v14, 0
	v_add3_u32 v15, v15, v16, v17
	v_add_u32_e32 v16, 40, v3
	v_ashrrev_i32_e32 v17, 31, v16
	v_mul_lo_u32 v18, s4, v17
	v_mul_lo_u32 v19, s5, v16
	v_mad_u64_u32 v[16:17], s[6:7], s4, v16, 0
	v_add3_u32 v17, v17, v18, v19
	v_add_u32_e32 v18, 48, v3
	v_ashrrev_i32_e32 v19, 31, v18
	v_mul_lo_u32 v22, s4, v19
	v_mul_lo_u32 v23, s5, v18
	v_mad_u64_u32 v[18:19], s[6:7], s4, v18, 0
	v_add3_u32 v19, v19, v22, v23
	v_add_u32_e32 v22, 56, v3
	v_ashrrev_i32_e32 v23, 31, v22
	v_mul_lo_u32 v24, s4, v23
	v_mul_lo_u32 v25, s5, v22
	v_mad_u64_u32 v[22:23], s[6:7], s4, v22, 0
	v_lshl_add_u64 v[4:5], v[4:5], 2, v[12:13]
	v_lshl_add_u64 v[6:7], v[6:7], 2, v[12:13]
	v_lshl_add_u64 v[8:9], v[8:9], 2, v[12:13]
	v_lshl_add_u64 v[10:11], v[10:11], 2, v[12:13]
	v_lshl_add_u64 v[14:15], v[14:15], 2, v[12:13]
	v_add3_u32 v23, v23, v24, v25
	v_lshl_add_u64 v[16:17], v[16:17], 2, v[12:13]
	v_lshl_add_u64 v[18:19], v[18:19], 2, v[12:13]
	v_lshl_add_u64 v[22:23], v[22:23], 2, v[12:13]
	global_load_dword v4, v[4:5], off nt
	s_nop 0
	global_load_dword v5, v[6:7], off nt
	s_nop 0
	global_load_dword v6, v[8:9], off nt
	global_load_dword v7, v[10:11], off nt
	s_nop 0
	global_load_dword v8, v[14:15], off nt
	global_load_dword v9, v[16:17], off nt
	global_load_dword v10, v[18:19], off nt
	global_load_dword v11, v[22:23], off nt
	v_add_u32_e32 v14, 64, v3
	v_ashrrev_i32_e32 v15, 31, v14
	v_mul_lo_u32 v16, s4, v15
	v_mul_lo_u32 v17, s5, v14
	v_mad_u64_u32 v[14:15], s[6:7], s4, v14, 0
	v_add3_u32 v15, v15, v16, v17
	v_add_u32_e32 v16, 0x48, v3
	v_ashrrev_i32_e32 v17, 31, v16
	v_mul_lo_u32 v18, s4, v17
	v_mul_lo_u32 v19, s5, v16
	v_mad_u64_u32 v[16:17], s[6:7], s4, v16, 0
	v_add3_u32 v17, v17, v18, v19
	v_add_u32_e32 v18, 0x50, v3
	v_ashrrev_i32_e32 v19, 31, v18
	v_mul_lo_u32 v22, s4, v19
	v_mul_lo_u32 v23, s5, v18
	v_mad_u64_u32 v[18:19], s[6:7], s4, v18, 0
	v_add3_u32 v19, v19, v22, v23
	v_add_u32_e32 v22, 0x58, v3
	v_ashrrev_i32_e32 v23, 31, v22
	v_mul_lo_u32 v24, s4, v23
	v_mul_lo_u32 v25, s5, v22
	v_mad_u64_u32 v[22:23], s[6:7], s4, v22, 0
	v_add3_u32 v23, v23, v24, v25
	v_add_u32_e32 v24, 0x60, v3
	v_ashrrev_i32_e32 v25, 31, v24
	v_mul_lo_u32 v26, s4, v25
	v_mul_lo_u32 v27, s5, v24
	v_mad_u64_u32 v[24:25], s[6:7], s4, v24, 0
	v_add3_u32 v25, v25, v26, v27
	v_add_u32_e32 v26, 0x68, v3
	v_ashrrev_i32_e32 v27, 31, v26
	v_mul_lo_u32 v28, s4, v27
	v_mul_lo_u32 v29, s5, v26
	v_mad_u64_u32 v[26:27], s[6:7], s4, v26, 0
	v_add3_u32 v27, v27, v28, v29
	v_add_u32_e32 v28, 0x70, v3
	v_ashrrev_i32_e32 v29, 31, v28
	v_mul_lo_u32 v30, s4, v29
	v_mul_lo_u32 v31, s5, v28
	v_mad_u64_u32 v[28:29], s[6:7], s4, v28, 0
	v_add_u32_e32 v3, 0x78, v3
	v_add3_u32 v29, v29, v30, v31
	v_ashrrev_i32_e32 v30, 31, v3
	v_mul_lo_u32 v32, s4, v30
	v_mul_lo_u32 v33, s5, v3
	v_mad_u64_u32 v[30:31], s[4:5], s4, v3, 0
	v_lshl_add_u64 v[14:15], v[14:15], 2, v[12:13]
	v_lshl_add_u64 v[16:17], v[16:17], 2, v[12:13]
	v_lshl_add_u64 v[18:19], v[18:19], 2, v[12:13]
	v_add3_u32 v31, v31, v32, v33
	v_lshl_add_u64 v[22:23], v[22:23], 2, v[12:13]
	v_lshl_add_u64 v[24:25], v[24:25], 2, v[12:13]
	v_lshl_add_u64 v[26:27], v[26:27], 2, v[12:13]
	v_lshl_add_u64 v[28:29], v[28:29], 2, v[12:13]
	v_lshl_add_u64 v[30:31], v[30:31], 2, v[12:13]
	global_load_dword v12, v[14:15], off nt
	global_load_dword v13, v[16:17], off nt
	s_nop 0
	global_load_dword v14, v[18:19], off nt
	global_load_dword v15, v[22:23], off nt
	global_load_dword v16, v[24:25], off nt
	global_load_dword v17, v[26:27], off nt
	s_nop 0
	global_load_dword v18, v[28:29], off nt
	global_load_dword v19, v[30:31], off nt
	v_ashrrev_i32_e32 v22, 3, v2
	v_lshlrev_b32_e32 v2, 4, v2
	s_movk_i32 s4, 0x104
	v_and_b32_e32 v26, 0x70, v2
	v_mul_lo_u32 v2, v21, s4
	s_add_u32 s4, s58, 0x4c00000
	s_addc_u32 s5, s59, 0
	s_add_u32 s6, s58, 0x2000000
	s_addc_u32 s7, s59, 0
	v_add_u32_e32 v0, 0, v0
	v_lshl_add_u32 v3, v22, 2, 0
	v_mul_u32_u24_e32 v24, 0x104, v26
	s_add_u32 s8, s58, 0x1800000
	s_addc_u32 s9, s59, 0
	v_add_u32_e32 v23, v0, v2
	v_lshlrev_b32_e32 v2, 2, v20
	s_movk_i32 s24, 0xff00
	s_movk_i32 s25, 0x80
	s_movk_i32 s26, 0xc00
	s_movk_i32 s27, 0x3ff
	v_add_u32_e32 v24, v3, v24
	v_lshlrev_b32_e32 v0, 1, v26
	v_mov_b32_e32 v25, 0x3e38aa3b
	v_mov_b32_e32 v26, 0x3e0293ee
	s_mov_b32 s28, s52
	s_branch .LBB0_24

; DEV void cvt_weights(const Params& p, int layer) {
;     ...
;     if (j.g) {
; #pragma unroll
;       for (int i = 0; i < 16; ++i) r[i] *= j.g[j.tk * 128 + kl0 + 8 * i]; }
.LBB0_24:
	s_cmp_eq_u64 s[2:3], 0
	s_cbranch_scc1 .LBB0_26
	v_lshl_add_u32 v28, s20, 7, v21
	v_ashrrev_i32_e32 v29, 31, v28
	v_lshl_add_u64 v[28:29], v[28:29], 2, s[2:3]
	global_load_dword v30, v[28:29], off offset:256 nt
	global_load_dword v31, v[28:29], off offset:288 nt
	global_load_dword v32, v[28:29], off offset:320 nt
	global_load_dword v33, v[28:29], off offset:352 nt
	global_load_dword v34, v[28:29], off offset:384 nt
	global_load_dword v35, v[28:29], off offset:416 nt
	global_load_dword v36, v[28:29], off offset:448 nt
	global_load_dword v37, v[28:29], off offset:480 nt
	global_load_dword v38, v[28:29], off offset:64 nt
	global_load_dword v39, v[28:29], off offset:96 nt
	global_load_dword v40, v[28:29], off offset:128 nt
	global_load_dword v42, v[28:29], off offset:192 nt
	global_load_dword v43, v[28:29], off offset:224 nt
	global_load_dword v41, v[28:29], off offset:160 nt
	global_load_dword v44, v[28:29], off nt
	global_load_dword v45, v[28:29], off offset:32 nt
	s_waitcnt vmcnt(14)
	v_pk_mul_f32 v[12:13], v[12:13], v[30:31]
	s_waitcnt vmcnt(12)
	v_pk_mul_f32 v[14:15], v[14:15], v[32:33]
	s_waitcnt vmcnt(10)
	v_pk_mul_f32 v[16:17], v[16:17], v[34:35]
	s_waitcnt vmcnt(8)
	v_pk_mul_f32 v[18:19], v[18:19], v[36:37]
	s_waitcnt vmcnt(6)
	v_pk_mul_f32 v[6:7], v[6:7], v[38:39]
	s_waitcnt vmcnt(3)
	v_pk_mul_f32 v[10:11], v[10:11], v[42:43]
	s_waitcnt vmcnt(2)
	v_pk_mul_f32 v[8:9], v[8:9], v[40:41]
	s_waitcnt vmcnt(0)
	v_pk_mul_f32 v[4:5], v[4:5], v[44:45]

; DEV void cvt_weights(const Params& p, int layer) {
;     ...
;     const CvtJob c = j; const int un = u + gridDim.x; const bool more = un < TOT;
;     if (more) { j = cvt_job(p, layer, un);
; #pragma unroll
;       for (int i = 0; i < 16; ++i) r[i] = j.W[(size_t)(j.tk * 128 + kl0 + 8 * i) * j.N + j.tn * 64 + nl]; }
.LBB0_41:
	s_lshl_b32 s18, s30, 6
	s_ashr_i32 s19, s18, 31
	s_lshl_b64 s[18:19], s[18:19], 2
	s_add_u32 s16, s16, s18
	v_lshl_add_u32 v20, s29, 7, v21
	s_addc_u32 s17, s17, s19
	v_mov_b32_e32 v3, v1
	v_lshl_add_u64 v[12:13], s[16:17], 0, v[2:3]
	v_ashrrev_i32_e32 v3, 31, v20
	v_mul_lo_u32 v3, s14, v3
	v_mul_lo_u32 v6, s15, v20
	v_mad_u64_u32 v[4:5], s[16:17], s14, v20, 0
	v_add3_u32 v5, v5, v3, v6
	v_add_u32_e32 v3, 8, v20
	v_ashrrev_i32_e32 v6, 31, v3
	v_mul_lo_u32 v8, s14, v6
	v_mul_lo_u32 v9, s15, v3
	v_mad_u64_u32 v[6:7], s[16:17], s14, v3, 0
	v_add_u32_e32 v3, 16, v20
	v_add3_u32 v7, v7, v8, v9
	v_ashrrev_i32_e32 v8, 31, v3
	v_mul_lo_u32 v10, s14, v8
	v_mul_lo_u32 v11, s15, v3
	v_mad_u64_u32 v[8:9], s[16:17], s14, v3, 0
	v_add_u32_e32 v3, 24, v20
	v_add3_u32 v9, v9, v10, v11
	v_ashrrev_i32_e32 v10, 31, v3
	v_mul_lo_u32 v14, s14, v10
	v_mul_lo_u32 v15, s15, v3
	v_mad_u64_u32 v[10:11], s[16:17], s14, v3, 0
	v_add_u32_e32 v3, 32, v20
	v_add3_u32 v11, v11, v14, v15
	v_ashrrev_i32_e32 v14, 31, v3
	v_mul_lo_u32 v16, s14, v14
	v_mul_lo_u32 v17, s15, v3
	v_mad_u64_u32 v[14:15], s[16:17], s14, v3, 0
	v_add_u32_e32 v3, 40, v20
	v_add3_u32 v15, v15, v16, v17
	v_ashrrev_i32_e32 v16, 31, v3
	v_mul_lo_u32 v18, s14, v16
	v_mul_lo_u32 v19, s15, v3
	v_mad_u64_u32 v[16:17], s[16:17], s14, v3, 0
	v_add_u32_e32 v3, 48, v20
	v_add3_u32 v17, v17, v18, v19
	v_ashrrev_i32_e32 v18, 31, v3
	v_mul_lo_u32 v27, s14, v18
	v_mul_lo_u32 v28, s15, v3
	v_mad_u64_u32 v[18:19], s[16:17], s14, v3, 0
	v_add_u32_e32 v3, 56, v20
	v_add3_u32 v19, v19, v27, v28
	v_ashrrev_i32_e32 v27, 31, v3
	v_mul_lo_u32 v27, s14, v27
	v_mul_lo_u32 v30, s15, v3
	v_mad_u64_u32 v[28:29], s[16:17], s14, v3, 0
	v_lshl_add_u64 v[4:5], v[4:5], 2, v[12:13]
	v_lshl_add_u64 v[6:7], v[6:7], 2, v[12:13]
	v_lshl_add_u64 v[8:9], v[8:9], 2, v[12:13]
	v_lshl_add_u64 v[10:11], v[10:11], 2, v[12:13]
	v_lshl_add_u64 v[14:15], v[14:15], 2, v[12:13]
	v_add3_u32 v29, v29, v27, v30
	v_add_u32_e32 v3, 64, v20
	v_lshl_add_u64 v[16:17], v[16:17], 2, v[12:13]
	v_lshl_add_u64 v[18:19], v[18:19], 2, v[12:13]
	v_lshl_add_u64 v[28:29], v[28:29], 2, v[12:13]
	global_load_dword v4, v[4:5], off nt
	s_nop 0
	global_load_dword v5, v[6:7], off nt
	s_nop 0
	global_load_dword v6, v[8:9], off nt
	global_load_dword v7, v[10:11], off nt
	s_nop 0
	global_load_dword v8, v[14:15], off nt
	global_load_dword v9, v[16:17], off nt
	global_load_dword v10, v[18:19], off nt
	global_load_dword v11, v[28:29], off nt
	v_ashrrev_i32_e32 v14, 31, v3
	v_mul_lo_u32 v16, s14, v14
	v_mul_lo_u32 v17, s15, v3
	v_mad_u64_u32 v[14:15], s[16:17], s14, v3, 0
	v_add_u32_e32 v3, 0x48, v20
	v_add3_u32 v15, v15, v16, v17
	v_ashrrev_i32_e32 v16, 31, v3
	v_mul_lo_u32 v18, s14, v16
	v_mul_lo_u32 v19, s15, v3
	v_mad_u64_u32 v[16:17], s[16:17], s14, v3, 0
	v_add_u32_e32 v3, 0x50, v20
	v_add3_u32 v17, v17, v18, v19
	v_ashrrev_i32_e32 v18, 31, v3
	v_mul_lo_u32 v27, s14, v18
	v_mul_lo_u32 v28, s15, v3
	v_mad_u64_u32 v[18:19], s[16:17], s14, v3, 0
	v_add_u32_e32 v3, 0x58, v20
	v_add3_u32 v19, v19, v27, v28
	v_ashrrev_i32_e32 v27, 31, v3
	v_mul_lo_u32 v27, s14, v27
	v_mul_lo_u32 v30, s15, v3
	v_mad_u64_u32 v[28:29], s[16:17], s14, v3, 0
	v_add_u32_e32 v3, 0x60, v20
	v_add3_u32 v29, v29, v27, v30
	v_ashrrev_i32_e32 v27, 31, v3
	v_mul_lo_u32 v27, s14, v27
	v_mul_lo_u32 v32, s15, v3
	v_mad_u64_u32 v[30:31], s[16:17], s14, v3, 0
	v_add_u32_e32 v3, 0x68, v20
	v_add3_u32 v31, v31, v27, v32
	v_ashrrev_i32_e32 v27, 31, v3
	v_mul_lo_u32 v27, s14, v27
	v_mul_lo_u32 v34, s15, v3
	v_mad_u64_u32 v[32:33], s[16:17], s14, v3, 0
	v_add_u32_e32 v3, 0x70, v20
	v_add3_u32 v33, v33, v27, v34
	v_ashrrev_i32_e32 v27, 31, v3
	v_mul_lo_u32 v36, s15, v3
	v_mad_u64_u32 v[34:35], s[16:17], s14, v3, 0
	v_add_u32_e32 v3, 0x78, v20
	v_mul_lo_u32 v27, s14, v27
	v_ashrrev_i32_e32 v20, 31, v3
	v_add3_u32 v35, v35, v27, v36
	v_mul_lo_u32 v20, s14, v20
	v_mul_lo_u32 v27, s15, v3
	v_mad_u64_u32 v[36:37], s[14:15], s14, v3, 0
	v_lshl_add_u64 v[14:15], v[14:15], 2, v[12:13]
	v_lshl_add_u64 v[16:17], v[16:17], 2, v[12:13]
	v_lshl_add_u64 v[18:19], v[18:19], 2, v[12:13]
	v_add3_u32 v37, v37, v20, v27
	v_lshl_add_u64 v[28:29], v[28:29], 2, v[12:13]
	v_lshl_add_u64 v[30:31], v[30:31], 2, v[12:13]
	v_lshl_add_u64 v[32:33], v[32:33], 2, v[12:13]
	v_lshl_add_u64 v[34:35], v[34:35], 2, v[12:13]
	v_lshl_add_u64 v[36:37], v[36:37], 2, v[12:13]
	global_load_dword v12, v[14:15], off nt
	global_load_dword v13, v[16:17], off nt
	s_nop 0
	global_load_dword v14, v[18:19], off nt
	global_load_dword v15, v[28:29], off nt
	global_load_dword v16, v[30:31], off nt
	global_load_dword v17, v[32:33], off nt
	s_nop 0
	global_load_dword v18, v[34:35], off nt
	global_load_dword v19, v[36:37], off nt

; DEV int lv(int x) { asm volatile("" : "+v"(x)); return x; }
; DEV void cvt_weights(const Params& p, int layer) {
;     ...
;   float* tile = (float*)shm_raw;
;   const int t = lv(threadIdx.x), nl = t & 63, kl0 = t >> 6;
;   const int nl2 = t >> 3, kc = (t & 7) * 16;
;   float r[16];
;   int u = blockIdx.x;
;   if (u >= TOT) return;
;   CvtJob j = cvt_job(p, layer, u);
; #pragma unroll
;   for (int i = 0; i < 16; ++i) r[i] = j.W[(size_t)(j.tk * 128 + kl0 + 8 * i) * j.N + j.tn * 64 + nl];
.LBB0_781:
	s_lshl_b32 s12, s21, 6
	s_ashr_i32 s13, s12, 31
	s_lshl_b64 s[12:13], s[12:13], 2
	v_and_b32_e32 v18, 63, v0
	v_ashrrev_i32_e32 v19, 6, v0
	s_add_u32 s10, s10, s12
	v_lshl_add_u32 v1, s19, 7, v19
	s_addc_u32 s11, s11, s13
	v_lshlrev_b32_e32 v192, 2, v18
	v_lshl_add_u64 v[20:21], s[10:11], 0, v[192:193]
	v_mad_i64_i32 v[2:3], s[10:11], s8, v1, 0
	v_lshl_add_u64 v[2:3], v[2:3], 2, v[20:21]
	global_load_dword v2, v[2:3], off nt
	v_add_u32_e32 v3, 8, v1
	v_mad_i64_i32 v[4:5], s[10:11], s8, v3, 0
	v_lshl_add_u64 v[4:5], v[4:5], 2, v[20:21]
	global_load_dword v3, v[4:5], off nt
	v_add_u32_e32 v4, 16, v1
	v_mad_i64_i32 v[4:5], s[10:11], s8, v4, 0
	v_lshl_add_u64 v[4:5], v[4:5], 2, v[20:21]
	global_load_dword v4, v[4:5], off nt
	v_add_u32_e32 v5, 24, v1
	v_mad_i64_i32 v[6:7], s[10:11], s8, v5, 0
	v_lshl_add_u64 v[6:7], v[6:7], 2, v[20:21]
	global_load_dword v5, v[6:7], off nt
	v_add_u32_e32 v6, 32, v1
	v_mad_i64_i32 v[6:7], s[10:11], s8, v6, 0
	v_lshl_add_u64 v[6:7], v[6:7], 2, v[20:21]
	global_load_dword v6, v[6:7], off nt
	v_add_u32_e32 v7, 40, v1
	v_mad_i64_i32 v[8:9], s[10:11], s8, v7, 0
	v_lshl_add_u64 v[8:9], v[8:9], 2, v[20:21]
	global_load_dword v7, v[8:9], off nt
	v_add_u32_e32 v8, 48, v1
	v_mad_i64_i32 v[8:9], s[10:11], s8, v8, 0
	v_lshl_add_u64 v[8:9], v[8:9], 2, v[20:21]
	global_load_dword v8, v[8:9], off nt
	v_add_u32_e32 v9, 56, v1
	v_mad_i64_i32 v[10:11], s[10:11], s8, v9, 0
	v_lshl_add_u64 v[10:11], v[10:11], 2, v[20:21]
	global_load_dword v9, v[10:11], off nt
	v_add_u32_e32 v10, 64, v1
	v_mad_i64_i32 v[10:11], s[10:11], s8, v10, 0
	v_lshl_add_u64 v[10:11], v[10:11], 2, v[20:21]
	global_load_dword v10, v[10:11], off nt
	v_add_u32_e32 v11, 0x48, v1
	v_mad_i64_i32 v[12:13], s[10:11], s8, v11, 0
	v_lshl_add_u64 v[12:13], v[12:13], 2, v[20:21]
	global_load_dword v11, v[12:13], off nt
	v_add_u32_e32 v12, 0x50, v1
	v_mad_i64_i32 v[12:13], s[10:11], s8, v12, 0
	v_lshl_add_u64 v[12:13], v[12:13], 2, v[20:21]
	global_load_dword v12, v[12:13], off nt
	v_add_u32_e32 v13, 0x58, v1
	v_mad_i64_i32 v[14:15], s[10:11], s8, v13, 0
	v_lshl_add_u64 v[14:15], v[14:15], 2, v[20:21]
	global_load_dword v13, v[14:15], off nt
	v_add_u32_e32 v14, 0x60, v1
	v_mad_i64_i32 v[14:15], s[10:11], s8, v14, 0
	v_lshl_add_u64 v[14:15], v[14:15], 2, v[20:21]
	global_load_dword v14, v[14:15], off nt
	v_add_u32_e32 v15, 0x68, v1
	v_mad_i64_i32 v[16:17], s[10:11], s8, v15, 0
	v_lshl_add_u64 v[16:17], v[16:17], 2, v[20:21]
	global_load_dword v15, v[16:17], off nt
	v_add_u32_e32 v16, 0x70, v1
	v_add_u32_e32 v1, 0x78, v1
	v_mad_i64_i32 v[16:17], s[10:11], s8, v16, 0
	v_mad_i64_i32 v[22:23], s[8:9], s8, v1, 0
	v_lshl_add_u64 v[16:17], v[16:17], 2, v[20:21]
	v_lshl_add_u64 v[20:21], v[22:23], 2, v[20:21]
	global_load_dword v16, v[16:17], off nt
	s_movk_i32 s8, 0x104
	global_load_dword v17, v[20:21], off nt
	v_ashrrev_i32_e32 v20, 3, v0
	v_lshlrev_b32_e32 v0, 4, v0
	v_and_b32_e32 v24, 0x70, v0
	v_add_u32_e32 v0, 0, v192
	v_lshl_add_u32 v1, v20, 2, 0
	v_mul_lo_u32 v21, v19, s8
	v_mul_u32_u24_e32 v22, 0x104, v24
	v_add_u32_e32 v21, v0, v21
	v_lshlrev_b32_e32 v0, 2, v18
	v_add_u32_e32 v22, v1, v22
	v_lshlrev_b32_e32 v192, 1, v24
	s_mov_b32 s22, s52
	s_branch .LBB0_784

; DEV void cvt_weights(const Params& p, int layer) {
;     ...
;     if (j.g) {
; #pragma unroll
;       for (int i = 0; i < 16; ++i) r[i] *= j.g[j.tk * 128 + kl0 + 8 * i]; }
.LBB0_784:
	s_cmp_eq_u64 s[6:7], 0
	s_cbranch_scc1 .LBB0_786
	v_lshl_add_u32 v24, s19, 7, v19
	v_ashrrev_i32_e32 v25, 31, v24
	v_lshl_add_u64 v[24:25], v[24:25], 2, s[6:7]
	global_load_dword v26, v[24:25], off offset:256 nt
	global_load_dword v27, v[24:25], off offset:288 nt
	global_load_dword v28, v[24:25], off offset:320 nt
	global_load_dword v29, v[24:25], off offset:352 nt
	global_load_dword v30, v[24:25], off offset:384 nt
	global_load_dword v31, v[24:25], off offset:416 nt
	global_load_dword v32, v[24:25], off offset:448 nt
	s_waitcnt lgkmcnt(0)
	global_load_dword v33, v[24:25], off offset:480 nt
	global_load_dword v34, v[24:25], off offset:64 nt
	global_load_dword v35, v[24:25], off offset:96 nt
	global_load_dword v36, v[24:25], off offset:128 nt
	global_load_dword v38, v[24:25], off offset:192 nt
	global_load_dword v39, v[24:25], off offset:224 nt
	global_load_dword v37, v[24:25], off offset:160 nt
	global_load_dword v40, v[24:25], off nt
	global_load_dword v41, v[24:25], off offset:32 nt
	s_waitcnt vmcnt(14)
	v_pk_mul_f32 v[10:11], v[10:11], v[26:27]
	s_waitcnt vmcnt(12)
	v_pk_mul_f32 v[12:13], v[12:13], v[28:29]
	s_waitcnt vmcnt(10)
	v_pk_mul_f32 v[14:15], v[14:15], v[30:31]
	s_waitcnt vmcnt(8)
	v_pk_mul_f32 v[16:17], v[16:17], v[32:33]
	s_waitcnt vmcnt(6)
	v_pk_mul_f32 v[4:5], v[4:5], v[34:35]
	s_waitcnt vmcnt(3)
	v_pk_mul_f32 v[8:9], v[8:9], v[38:39]
	s_waitcnt vmcnt(2)
	v_pk_mul_f32 v[6:7], v[6:7], v[36:37]
	s_waitcnt vmcnt(0)
	v_pk_mul_f32 v[2:3], v[2:3], v[40:41]

; DEV void cvt_weights(const Params& p, int layer) {
;     ...
;     const CvtJob c = j; const int un = u + gridDim.x; const bool more = un < TOT;
;     if (more) { j = cvt_job(p, layer, un);
; #pragma unroll
;       for (int i = 0; i < 16; ++i) r[i] = j.W[(size_t)(j.tk * 128 + kl0 + 8 * i) * j.N + j.tn * 64 + nl]; }
.LBB0_802:
	s_lshl_b32 s16, s24, 6
	s_ashr_i32 s17, s16, 31
	s_lshl_b64 s[16:17], s[16:17], 2
	s_add_u32 s14, s14, s16
	v_lshl_add_u32 v18, s23, 7, v19
	s_addc_u32 s15, s15, s17
	v_mov_b32_e32 v1, v193
	v_lshl_add_u64 v[24:25], s[14:15], 0, v[0:1]
	v_ashrrev_i32_e32 v1, 31, v18
	v_mul_lo_u32 v1, s12, v1
	v_mul_lo_u32 v4, s13, v18
	v_mad_u64_u32 v[2:3], s[14:15], s12, v18, 0
	v_add3_u32 v3, v3, v1, v4
	v_lshl_add_u64 v[2:3], v[2:3], 2, v[24:25]
	v_add_u32_e32 v1, 8, v18
	global_load_dword v2, v[2:3], off nt
	v_ashrrev_i32_e32 v3, 31, v1
	v_mul_lo_u32 v3, s12, v3
	v_mul_lo_u32 v6, s13, v1
	v_mad_u64_u32 v[4:5], s[14:15], s12, v1, 0
	v_add3_u32 v5, v5, v3, v6
	v_lshl_add_u64 v[4:5], v[4:5], 2, v[24:25]
	v_add_u32_e32 v1, 16, v18
	global_load_dword v3, v[4:5], off nt
	v_ashrrev_i32_e32 v4, 31, v1
	v_mul_lo_u32 v6, s12, v4
	v_mul_lo_u32 v7, s13, v1
	v_mad_u64_u32 v[4:5], s[14:15], s12, v1, 0
	v_add3_u32 v5, v5, v6, v7
	v_lshl_add_u64 v[4:5], v[4:5], 2, v[24:25]
	v_add_u32_e32 v1, 24, v18
	global_load_dword v4, v[4:5], off nt
	v_ashrrev_i32_e32 v5, 31, v1
	v_mul_lo_u32 v5, s12, v5
	v_mul_lo_u32 v8, s13, v1
	v_mad_u64_u32 v[6:7], s[14:15], s12, v1, 0
	v_add3_u32 v7, v7, v5, v8
	v_lshl_add_u64 v[6:7], v[6:7], 2, v[24:25]
	v_add_u32_e32 v1, 32, v18
	global_load_dword v5, v[6:7], off nt
	v_ashrrev_i32_e32 v6, 31, v1
	v_mul_lo_u32 v8, s12, v6
	v_mul_lo_u32 v9, s13, v1
	v_mad_u64_u32 v[6:7], s[14:15], s12, v1, 0
	v_add3_u32 v7, v7, v8, v9
	v_lshl_add_u64 v[6:7], v[6:7], 2, v[24:25]
	v_add_u32_e32 v1, 40, v18
	global_load_dword v6, v[6:7], off nt
	v_ashrrev_i32_e32 v7, 31, v1
	v_mul_lo_u32 v7, s12, v7
	v_mul_lo_u32 v10, s13, v1
	v_mad_u64_u32 v[8:9], s[14:15], s12, v1, 0
	v_add3_u32 v9, v9, v7, v10
	v_lshl_add_u64 v[8:9], v[8:9], 2, v[24:25]
	v_add_u32_e32 v1, 48, v18
	global_load_dword v7, v[8:9], off nt
	v_ashrrev_i32_e32 v8, 31, v1
	v_mul_lo_u32 v10, s12, v8
	v_mul_lo_u32 v11, s13, v1
	v_mad_u64_u32 v[8:9], s[14:15], s12, v1, 0
	v_add3_u32 v9, v9, v10, v11
	v_lshl_add_u64 v[8:9], v[8:9], 2, v[24:25]
	v_add_u32_e32 v1, 56, v18
	global_load_dword v8, v[8:9], off nt
	v_ashrrev_i32_e32 v9, 31, v1
	v_mul_lo_u32 v9, s12, v9
	v_mul_lo_u32 v12, s13, v1
	v_mad_u64_u32 v[10:11], s[14:15], s12, v1, 0
	v_add3_u32 v11, v11, v9, v12
	v_lshl_add_u64 v[10:11], v[10:11], 2, v[24:25]
	v_add_u32_e32 v1, 64, v18
	global_load_dword v9, v[10:11], off nt
	v_ashrrev_i32_e32 v10, 31, v1
	v_mul_lo_u32 v12, s12, v10
	v_mul_lo_u32 v13, s13, v1
	v_mad_u64_u32 v[10:11], s[14:15], s12, v1, 0
	v_add3_u32 v11, v11, v12, v13
	v_lshl_add_u64 v[10:11], v[10:11], 2, v[24:25]
	v_add_u32_e32 v1, 0x48, v18
	global_load_dword v10, v[10:11], off nt
	v_ashrrev_i32_e32 v11, 31, v1
	v_mul_lo_u32 v11, s12, v11
	v_mul_lo_u32 v14, s13, v1
	v_mad_u64_u32 v[12:13], s[14:15], s12, v1, 0
	v_add3_u32 v13, v13, v11, v14
	v_lshl_add_u64 v[12:13], v[12:13], 2, v[24:25]
	v_add_u32_e32 v1, 0x50, v18
	global_load_dword v11, v[12:13], off nt
	v_ashrrev_i32_e32 v12, 31, v1
	v_mul_lo_u32 v14, s12, v12
	v_mul_lo_u32 v15, s13, v1
	v_mad_u64_u32 v[12:13], s[14:15], s12, v1, 0
	v_add3_u32 v13, v13, v14, v15
	v_lshl_add_u64 v[12:13], v[12:13], 2, v[24:25]
	v_add_u32_e32 v1, 0x58, v18
	global_load_dword v12, v[12:13], off nt
	v_ashrrev_i32_e32 v13, 31, v1
	v_mul_lo_u32 v13, s12, v13
	v_mul_lo_u32 v16, s13, v1
	v_mad_u64_u32 v[14:15], s[14:15], s12, v1, 0
	v_add3_u32 v15, v15, v13, v16
	v_lshl_add_u64 v[14:15], v[14:15], 2, v[24:25]
	v_add_u32_e32 v1, 0x60, v18
	global_load_dword v13, v[14:15], off nt
	v_ashrrev_i32_e32 v14, 31, v1
	v_mul_lo_u32 v16, s12, v14
	v_mul_lo_u32 v17, s13, v1
	v_mad_u64_u32 v[14:15], s[14:15], s12, v1, 0
	v_add3_u32 v15, v15, v16, v17
	v_lshl_add_u64 v[14:15], v[14:15], 2, v[24:25]
	v_add_u32_e32 v1, 0x68, v18
	global_load_dword v14, v[14:15], off nt
	v_ashrrev_i32_e32 v15, 31, v1
	v_mul_lo_u32 v15, s12, v15
	v_mul_lo_u32 v23, s13, v1
	v_mad_u64_u32 v[16:17], s[14:15], s12, v1, 0
	v_add3_u32 v17, v17, v15, v23
	v_lshl_add_u64 v[16:17], v[16:17], 2, v[24:25]
	v_add_u32_e32 v1, 0x70, v18
	global_load_dword v15, v[16:17], off nt
	v_ashrrev_i32_e32 v16, 31, v1
	v_mul_lo_u32 v23, s12, v16
	v_mul_lo_u32 v26, s13, v1
	v_mad_u64_u32 v[16:17], s[14:15], s12, v1, 0
	v_add3_u32 v17, v17, v23, v26
	v_lshl_add_u64 v[16:17], v[16:17], 2, v[24:25]
	v_add_u32_e32 v1, 0x78, v18
	global_load_dword v16, v[16:17], off nt
	v_ashrrev_i32_e32 v17, 31, v1
	v_mul_lo_u32 v17, s12, v17
	v_mul_lo_u32 v18, s13, v1
	v_mad_u64_u32 v[26:27], s[12:13], s12, v1, 0
	v_add3_u32 v27, v27, v17, v18
	v_lshl_add_u64 v[24:25], v[26:27], 2, v[24:25]
	global_load_dword v17, v[24:25], off nt
